# speedup vs baseline: 1.0028x; 1.0016x over previous
; __global__ void __launch_bounds__(512, 2) fwd_megakernel(Params p) {
;     ...
;         for (int u2 = blockIdx.x * 2; u2 < 2048; u2 += (u2 & 1) ? (int)gridDim.x * 2 - 1 : 1) {
;           const int ul = u2 >> 1, pass = u2 & 1;
;           int u = ul;
;           if (gridDim.x == 256) { const int it = ul >> 8, bq = ul & 255; u = (it >> 1) * 512 + (bq & 7) * 64 + (bq >> 3) + 32 * (it & 1); }
;           int h, rows0, seqb, seq;
;           if (u < 512) { const int qb = u & 63; h = u >> 6; rows0 = qb * 256; seqb = 0; seq = 16384; }
;           else { const int u3 = u - 512, qb = u3 & 63; h = u3 >> 6; seqb = TP + (qb >> 3) * 2048; rows0 = seqb + (qb & 7) * 256; seq = 2048; }
;           const int n = 2 * h + pass;
;           att::attn_body256(R0 + (size_t)rows0 * DM + n * 128, R1 + (size_t)seqb * DM + n * 128, R2 + (size_t)seqb * DM + h * 256,
;                             Od + (size_t)rows0 * DM + h * 256, seq, smem, lam, pass, Abuf + (size_t)rows0 * DM + h * 256, p.in[14]);
;           __syncthreads();
;         }
.LBB0_662:
	s_add_i32 s18, s0, s18
	s_cmpk_gt_i32 s18, 0x7ff
	s_barrier
	s_cbranch_scc1 .LBB0_684

; #define LAS __attribute__((address_space(3)))
; __device__ __forceinline__ int opaque_tid() { int t; asm volatile("v_mov_b32 %0, %1" : "=v"(t) : "v"(threadIdx.x)); return t; }
; __device__ __forceinline__ int v_rd_base(int lane) { return ((lane & 3) << 3) | (((lane >> 2) & 3) << 6) | (((lane >> 4) & 1) << 5) | (((lane >> 5) & 1) << 8); }
; __device__ __forceinline__ void attn_body256(const bf16_t* __restrict__ Qb, const bf16_t* __restrict__ Kh, const bf16_t* __restrict__ Vh,
;                                              bf16_t* Ob, int seq, unsigned char* lds, float lam, int MODE, bf16_t* Ab, const float* wsub) {
;   const int tid = opaque_tid(), wid = __builtin_amdgcn_readfirstlane(tid >> 6), lane = tid & 63, r32 = lane & 31, hi = lane >> 5;
;   LAS unsigned char* ldsl = (LAS unsigned char*)lds;
;   float* ws = (float*)(lds + A2_WS) + wid * 64; float* li_l = ws; float* al_l = ws + 32;
;   unsigned koff[2], voff[4];
; #pragma unroll
;   for (int i = 0; i < 2; ++i) { const int o = i * 8192 + tid * 16; const int row = o >> 8; const int colB = (o & 255) ^ ((row & 7) << 4);
;     koff[i] = (unsigned)(row * LDK + (colB >> 1));
;     const int sub = o >> 9, kk = (sub >> 2) * 8 + ((o & 511) >> 6), c = (sub & 3) * 32 + (((o & 511) >> 1) & 31);
;     const int k = (kk & ~0xC) | ((kk & 4) << 1) | ((kk & 8) >> 1);
;     voff[i] = (unsigned)(k * LDK + c); voff[2 + i] = (unsigned)(k * LDK + 128 + c); }
;     ...
;   const int NT = seq / KVBLK;
;   A2_DMA(0, 0); A2_DMA(1, 1);
;   float m_reg = -1e30f, l_reg = 0; f32x16 o[8] = {}; bf16x8 qr[8];
;   const bf16_t* Qw = Qb + (long)(wid * QBLK + r32) * LDQ + hi * 8;
; #pragma unroll
;   for (int d0 = 0; d0 < 8; ++d0) qr[d0] = *reinterpret_cast<const bf16x8*>(Qw + d0 * 16);
;   const int vb0 = (int)(uintptr_t)lds + v_rd_base(lane);
.LBB0_669:
	s_and_b32 s2, s18, 1
	s_lshl_b64 s[10:11], s[62:63], 11
	s_lshl_b64 s[6:7], s[62:63], 12
	s_add_u32 s9, s96, s6
	s_addc_u32 s12, s97, s7
	s_lshl_b32 s16, s8, 8
	s_lshl_b32 s6, s2, 7
	s_or_b32 s6, s16, s6
	s_ashr_i32 s7, s6, 31
	s_lshl_b64 s[14:15], s[6:7], 1
	s_add_u32 s6, s9, s14
	s_addc_u32 s7, s12, s15
	s_lshl_b64 s[8:9], s[0:1], 1
	s_add_u32 s0, s60, s8
	s_addc_u32 s1, s53, s9
	s_add_u32 s12, s0, s14
	s_addc_u32 s13, s1, s15
	v_mov_b32 v16, v231
	v_lshrrev_b32_e32 v245, 7, v231
	v_lshlrev_b32_e32 v245, 3, v245
	v_bfe_u32 v244, v231, 1, 3
	v_add_u32_e32 v245, v245, v244
	v_lshlrev_b32_e32 v245, 11, v245
	v_bfe_u32 v244, v231, 4, 3
	v_lshl_add_u32 v245, v244, 4, v245
	v_and_b32_e32 v244, 1, v231
	v_lshl_add_u32 v245, v244, 3, v245
	v_lshrrev_b32_e32 v239, 4, v231
	v_and_b32_e32 v244, 15, v239
	v_and_b32_e32 v242, 15, v231
	v_xor_b32_e32 v242, v242, v244
	v_lshlrev_b32_e32 v242, 3, v242
	v_lshl_add_u32 v239, v239, 11, v242
	s_add_u32 s20, s61, s8
	v_lshlrev_b32_e32 v17, 4, v16
	v_add_u32_e32 v6, 0x2000, v17
	s_addc_u32 s21, s68, s9
	s_ashr_i32 s17, s16, 31
	v_ashrrev_i32_e32 v8, 8, v6
	s_lshl_b64 s[0:1], s[16:17], 1
	v_and_b32_e32 v3, 0xf0, v17
	v_lshlrev_b32_e32 v6, 4, v8
	s_movk_i32 s26, 0x70
	s_add_u32 s16, s20, s0
	v_lshrrev_b32_e32 v0, 1, v16
	v_ashrrev_i32_e32 v2, 4, v16
	v_bitop3_b32 v3, v6, v3, s26 bitop3:0x6c
	s_addc_u32 s17, s21, s1
	v_readfirstlane_b32 s20, v16
	v_and_b32_e32 v22, 8, v0
	v_and_b32_e32 v0, 0x70, v16
	s_movk_i32 s21, 0xf0
	v_lshrrev_b32_e32 v4, 1, v2
	v_lshrrev_b32_e32 v3, 1, v3
	s_ashr_i32 s23, s20, 6
	v_bfe_u32 v18, v16, 2, 2
	v_lshlrev_b32_e32 v20, 3, v16
	v_bitop3_b32 v0, v17, v0, s21 bitop3:0x6c
	v_and_b32_e32 v4, 4, v4
	v_lshl_or_b32 v6, v8, 11, v3
	v_add_u32_e32 v6, 0x10000, v239
	v_and_b32_e32 v3, 0x1ffff0, v8
	v_lshrrev_b32_e32 v8, 1, v8
	v_and_b32_e32 v19, 0x60, v16
	v_and_b32_e32 v21, 24, v20
	v_or_b32_e32 v7, v22, v18
	v_lshrrev_b32_e32 v0, 1, v0
	v_and_or_b32 v23, v2, -16, v4
	v_and_b32_e32 v8, 4, v8
	s_lshl_b32 s21, s23, 10
	v_or_b32_e32 v5, v21, v19
	v_lshl_or_b32 v0, v2, 11, v0
	v_mov_b32_e32 v0, v239
	v_or_b32_e32 v2, v7, v23
	v_or3_b32 v3, v3, v8, v7
	s_add_i32 s21, s21, 0
	v_lshl_or_b32 v2, v2, 11, v5
	v_mov_b32_e32 v2, v245
	v_lshlrev_b32_e32 v24, 11, v3
	s_add_i32 s22, s21, 0x10000
	v_lshlrev_b64 v[12:13], 1, v[0:1]
	v_mov_b32_e32 v3, v1
	v_or_b32_e32 v4, 0x80, v2
	v_lshl_add_u64 v[14:15], s[12:13], 0, v[12:13]
	s_mov_b32 m0, s22
	v_lshlrev_b64 v[2:3], 1, v[2:3]
	s_add_i32 s24, s21, 0x4000
	global_load_lds_dwordx4 v[14:15], off
	v_lshl_add_u64 v[14:15], s[16:17], 0, v[2:3]
	s_mov_b32 m0, s21
	s_mov_b64 s[30:31], 0x100
	v_mov_b32_e32 v7, v1
	s_and_b32 s20, s20, 0x3fffffc0
	v_or_b32_e32 v8, v24, v5
	v_add_u32_e32 v8, 0x10000, v245
	global_load_lds_dwordx4 v[14:15], off
	v_lshl_add_u64 v[14:15], v[14:15], 0, s[30:31]
	s_mov_b32 m0, s24
	v_lshlrev_b64 v[6:7], 1, v[6:7]
	v_mov_b32_e32 v9, v1
	s_lshl_b32 s20, s20, 2
	v_or_b32_e32 v10, 0x80, v8
	global_load_lds_dwordx4 v[14:15], off
	v_lshl_add_u64 v[14:15], s[12:13], 0, v[6:7]
	s_add_i32 m0, s21, 0x12000
	v_lshlrev_b64 v[8:9], 1, v[8:9]
	s_add_i32 s20, s20, 0
	global_load_lds_dwordx4 v[14:15], off
	v_lshl_add_u64 v[14:15], s[16:17], 0, v[8:9]
	s_add_i32 m0, s21, 0x2000
	s_add_i32 s20, s20, 0x18000
	global_load_lds_dwordx4 v[14:15], off
	s_add_i32 m0, s21, 0x6000
	s_add_u32 s12, s12, 0x40000
	s_addc_u32 s13, s13, 0
	v_lshl_add_u64 v[14:15], v[14:15], 0, s[30:31]
	s_add_u32 s16, s16, 0x40000
	global_load_lds_dwordx4 v[14:15], off
	s_addc_u32 s17, s17, 0
	s_add_i32 m0, s21, 0x14000
	s_add_i32 s24, s21, 0x8000
	v_lshl_add_u64 v[14:15], s[12:13], 0, v[12:13]
	v_mov_b32_e32 v5, v1
	s_add_i32 s25, s21, 0xc000
	global_load_lds_dwordx4 v[14:15], off
	v_lshl_add_u64 v[2:3], s[16:17], 0, v[2:3]
	s_mov_b32 m0, s24
	v_mov_b32_e32 v11, v1
	global_load_lds_dwordx4 v[2:3], off
	v_lshl_add_u64 v[2:3], v[4:5], 1, s[16:17]
	s_mov_b32 m0, s25
	v_and_b32_e32 v228, 31, v16
	global_load_lds_dwordx4 v[2:3], off
	v_lshl_add_u64 v[2:3], s[12:13], 0, v[6:7]
	s_add_i32 m0, s21, 0x16000
	s_lshl_b32 s12, s23, 5
	global_load_lds_dwordx4 v[2:3], off
	v_lshl_add_u64 v[2:3], s[16:17], 0, v[8:9]
	s_add_i32 m0, s21, 0xa000
	v_bfe_u32 v229, v16, 5, 1
	global_load_lds_dwordx4 v[2:3], off
	v_lshl_add_u64 v[2:3], v[10:11], 1, s[16:17]
	s_add_i32 m0, s21, 0xe000
	v_lshlrev_b32_e32 v0, 4, v229
	global_load_lds_dwordx4 v[2:3], off
	v_and_b32_e32 v2, 15, v231
	v_or_b32_e32 v2, s12, v2
	v_mov_b32_e32 v3, 0
	v_lshlrev_b64 v[2:3], 12, v[2:3]
	v_lshl_add_u64 v[2:3], s[6:7], 0, v[2:3]
	v_bfe_u32 v194, v231, 4, 2
	v_lshlrev_b32_e32 v194, 4, v194
	v_mov_b32_e32 v195, 0
	v_lshl_add_u64 v[2:3], v[2:3], 0, v[194:195]
	global_load_dwordx4 v[162:165], v[2:3], off
	global_load_dwordx4 v[166:169], v[2:3], off offset:64
	global_load_dwordx4 v[170:173], v[2:3], off offset:128
	global_load_dwordx4 v[174:177], v[2:3], off offset:192
	v_mov_b32_e32 v194, 0x10000
	v_lshl_add_u64 v[2:3], v[2:3], 0, v[194:195]
	global_load_dwordx4 v[178:181], v[2:3], off
	global_load_dwordx4 v[182:185], v[2:3], off offset:64
	global_load_dwordx4 v[186:189], v[2:3], off offset:128
	global_load_dwordx4 v[190:193], v[2:3], off offset:192
	v_and_b32_e32 v8, 0x70, v17
	s_movk_i32 s6, 0x60
	v_bitop3_b32 v236, v0, v8, s6 bitop3:0x36
	s_movk_i32 s6, 0x80
	v_bitop3_b32 v237, v0, v8, s6 bitop3:0x36
	s_movk_i32 s6, 0xa0
	v_bitop3_b32 v240, v0, v8, s6 bitop3:0x36
; #define SBAR() __builtin_amdgcn_sched_barrier(0)
; __device__ __forceinline__ int v_rd_base(int lane) { return ((lane & 3) << 3) | (((lane >> 2) & 3) << 6) | (((lane >> 4) & 1) << 5) | (((lane >> 5) & 1) << 8); }
; __device__ __forceinline__ void qkt(f32x16& p0, f32x16& p1, const bf16_t* Ks, const bf16x8* qr, int r32, int hi) {
;   p0 = f32x16{}; p1 = f32x16{};
;   for (int d0 = 0; d0 < 8; ++d0) { int cb = (d0 * 16 + hi * 8) * 2;
;     bf16x8 b0 = *reinterpret_cast<const bf16x8*>((const char*)Ks + KSWZ(r32, cb));
;     bf16x8 b1 = *reinterpret_cast<const bf16x8*>((const char*)Ks + KSWZ(32 + r32, cb));
; __device__ __forceinline__ void attn_body256(const bf16_t* __restrict__ Qb, const bf16_t* __restrict__ Kh, const bf16_t* __restrict__ Vh,
;                                              bf16_t* Ob, int seq, unsigned char* lds, float lam, int MODE, bf16_t* Ab, const float* wsub) {
;     ...
;   float m_reg = -1e30f, l_reg = 0; f32x16 o[8] = {}; bf16x8 qr[8];
;   const bf16_t* Qw = Qb + (long)(wid * QBLK + r32) * LDQ + hi * 8;
; #pragma unroll
;   for (int d0 = 0; d0 < 8; ++d0) qr[d0] = *reinterpret_cast<const bf16x8*>(Qw + d0 * 16);
;   const int vb0 = (int)(uintptr_t)lds + v_rd_base(lane);
;   asm volatile("s_waitcnt vmcnt(0)" ::: "memory"); __syncthreads();
;   for (int j = 0; j < NT; ++j) {
;     const int b = j & 1;
;     f32x16 p0, p1; float mn, alpha; bf16x8 pa0, pa1, pa2, pa3;
;     SBAR(); qkt(p0, p1, (const bf16_t*)(lds + A2_KOFF + b * A2_KBUF), qr, r32, hi);
	s_movk_i32 s6, 0xc0
	s_cmp_lg_u32 0, -1
	v_and_b32_e32 v2, 63, v16
	v_lshlrev_b32_e32 v3, 1, v16
	v_and_b32_e32 v4, 0x118, v20
	v_bitop3_b32 v241, v0, v8, s6 bitop3:0x36
	s_movk_i32 s6, 0xe0
	s_cselect_b32 s16, 0, 0
	s_lshl_b32 s23, s19, 18
	v_and_b32_e32 v5, 0xc0, v17
	v_bitop3_b32 v247, v0, v8, s6 bitop3:0x36
	v_cmp_gt_u32_e64 s[6:7], 32, v2
	v_and_or_b32 v2, v3, 32, v4
	s_add_u32 s14, s8, s14
	v_add3_u32 v248, v5, s16, v2
	s_addc_u32 s15, s9, s15
	v_readlane_b32 s16, v254, 41
	s_add_u32 s14, s16, s14
	v_readlane_b32 s16, v254, 42
	s_addc_u32 s15, s16, s15
	s_add_u32 s8, s8, s0
	s_addc_u32 s9, s9, s1
	v_or3_b32 v2, v23, v22, v18
	v_lshlrev_b32_e32 v2, 11, v2
	s_add_u32 s8, s88, s8
	v_or3_b32 v2, v2, v19, v21
	v_mov_b32_e32 v2, v245
	v_mov_b32_e32 v3, v1
	s_addc_u32 s9, s89, s9
	v_bitop3_b32 v232, v0, v17, s26 bitop3:0x78
	v_lshl_add_u64 v[224:225], v[2:3], 1, s[8:9]
	s_add_u32 s66, s8, 0x25480000
	s_addc_u32 s67, s9, 0
	v_or3_b32 v2, v24, v19, v21
	v_add_u32_e32 v2, 0x10000, v245
	v_mov_b32_e32 v16, v1
	v_mov_b32_e32 v17, v1
	v_bitop3_b32 v233, v0, v8, 32 bitop3:0x36
	v_bitop3_b32 v234, v0, v8, 64 bitop3:0x36
	v_lshl_add_u64 v[220:221], s[14:15], 0, v[12:13]
	v_lshl_add_u64 v[222:223], s[14:15], 0, v[6:7]
	v_lshl_add_u64 v[226:227], v[2:3], 1, s[8:9]
	v_mov_b32_e32 v2, v1
	v_mov_b32_e32 v4, v1
	v_mov_b32_e32 v5, v1
	v_mov_b32_e32 v6, v1
	v_mov_b32_e32 v7, v1
	v_mov_b32_e32 v8, v1
	v_mov_b32_e32 v9, v1
	v_mov_b32_e32 v10, v1
	v_mov_b32_e32 v12, v1
	v_mov_b32_e32 v13, v1
	v_mov_b32_e32 v14, v1
	v_mov_b32_e32 v15, v1
	v_mov_b64_e32 v[128:129], v[16:17]
	v_mov_b64_e32 v[112:113], v[16:17]
	v_mov_b64_e32 v[96:97], v[16:17]
	v_mov_b64_e32 v[80:81], v[16:17]
	v_mov_b64_e32 v[64:65], v[16:17]
	v_mov_b64_e32 v[48:49], v[16:17]
	v_mov_b64_e32 v[32:33], v[16:17]
	s_mov_b32 s13, 2
	v_lshlrev_b32_e32 v230, 8, v228
	v_lshl_add_u32 v238, v228, 2, s20
	v_mov_b32_e32 v250, 0
	v_mov_b32_e32 v249, 0xf149f2ca
	s_nop 0
	v_mov_b64_e32 v[126:127], v[14:15]
	v_mov_b64_e32 v[124:125], v[12:13]
	v_mov_b64_e32 v[122:123], v[10:11]
	v_mov_b64_e32 v[120:121], v[8:9]
	v_mov_b64_e32 v[118:119], v[6:7]
	v_mov_b64_e32 v[116:117], v[4:5]
	v_mov_b64_e32 v[114:115], v[2:3]
	v_mov_b64_e32 v[110:111], v[14:15]
	v_mov_b64_e32 v[108:109], v[12:13]
	v_mov_b64_e32 v[106:107], v[10:11]
	v_mov_b64_e32 v[104:105], v[8:9]
	v_mov_b64_e32 v[102:103], v[6:7]
	v_mov_b64_e32 v[100:101], v[4:5]
	v_mov_b64_e32 v[98:99], v[2:3]
	v_mov_b64_e32 v[94:95], v[14:15]
	v_mov_b64_e32 v[92:93], v[12:13]
	v_mov_b64_e32 v[90:91], v[10:11]
	v_mov_b64_e32 v[88:89], v[8:9]
	v_mov_b64_e32 v[86:87], v[6:7]
	v_mov_b64_e32 v[84:85], v[4:5]
	v_mov_b64_e32 v[82:83], v[2:3]
	v_mov_b64_e32 v[78:79], v[14:15]
	v_mov_b64_e32 v[76:77], v[12:13]
	v_mov_b64_e32 v[74:75], v[10:11]
	v_mov_b64_e32 v[72:73], v[8:9]
	v_mov_b64_e32 v[70:71], v[6:7]
	v_mov_b64_e32 v[68:69], v[4:5]
	v_mov_b64_e32 v[66:67], v[2:3]
	v_mov_b64_e32 v[62:63], v[14:15]
	v_mov_b64_e32 v[60:61], v[12:13]
	v_mov_b64_e32 v[58:59], v[10:11]
	v_mov_b64_e32 v[56:57], v[8:9]
	v_mov_b64_e32 v[54:55], v[6:7]
	v_mov_b64_e32 v[52:53], v[4:5]
	v_mov_b64_e32 v[50:51], v[2:3]
	v_mov_b64_e32 v[46:47], v[14:15]
	v_mov_b64_e32 v[44:45], v[12:13]
	v_mov_b64_e32 v[42:43], v[10:11]
	v_mov_b64_e32 v[40:41], v[8:9]
	v_mov_b64_e32 v[38:39], v[6:7]
	v_mov_b64_e32 v[36:37], v[4:5]
	v_mov_b64_e32 v[34:35], v[2:3]
	v_mov_b64_e32 v[30:31], v[14:15]
	v_mov_b64_e32 v[28:29], v[12:13]
	v_mov_b64_e32 v[26:27], v[10:11]
	v_mov_b64_e32 v[24:25], v[8:9]
	v_mov_b64_e32 v[22:23], v[6:7]
	v_mov_b64_e32 v[20:21], v[4:5]
	v_mov_b64_e32 v[18:19], v[2:3]
	v_and_b32_e32 v237, 15, v231
	v_bfe_u32 v240, v231, 4, 2
	v_add_u32_e32 v247, 0, v240
	v_xor_b32_e32 v247, v247, v237
	v_lshlrev_b32_e32 v247, 4, v247
	v_lshl_add_u32 v232, v237, 8, v247
	v_add_u32_e32 v247, 4, v240
	v_xor_b32_e32 v247, v247, v237
	v_lshlrev_b32_e32 v247, 4, v247
	v_lshl_add_u32 v233, v237, 8, v247
	v_add_u32_e32 v247, 8, v240
	v_xor_b32_e32 v247, v247, v237
	v_lshlrev_b32_e32 v247, 4, v247
	v_lshl_add_u32 v246, v237, 8, v247
	v_add_u32_e32 v247, 12, v240
	v_xor_b32_e32 v247, v247, v237
	v_lshlrev_b32_e32 v247, 4, v247
	v_lshl_add_u32 v249, v237, 8, v247
	v_and_b32_e32 v247, 1, v240
	v_lshlrev_b32_e32 v248, 7, v247
	v_lshrrev_b32_e32 v247, 1, v240
	v_lshl_add_u32 v248, v247, 11, v248
	v_bfe_u32 v247, v231, 2, 2
	v_lshl_add_u32 v248, v247, 5, v248
	v_and_b32_e32 v247, 3, v231
	v_lshl_add_u32 v248, v247, 3, v248
	v_mov_b32_e32 v250, 0
	v_mov_b32_e32 v234, 0
	v_lshlrev_b32_e32 v220, 1, v239
	v_add_u32_e32 v221, 0x20000, v220
	v_lshlrev_b32_e32 v222, 1, v245
	v_add_u32_e32 v223, 0x20000, v222
	s_add_i32 s23, s19, 2
	v_mov_b32_e32 v236, 0
	v_mov_b32_e32 v237, 0
	v_mov_b32_e32 v238, 0
	v_mov_b32_e32 v239, 0
	v_mov_b32_e32 v240, 0
	v_mov_b32_e32 v241, 0
	v_mov_b32_e32 v242, 0
	v_mov_b32_e32 v243, 0
	s_movk_i32 s62, 0x7fff
	s_waitcnt vmcnt(0) lgkmcnt(0)
	s_barrier
	s_mov_b32 s98, 0
	s_mov_b32 s99, 0x8000
	s_mov_b32 s100, 0x19000
	s_cmpk_ge_u32 s21, 0x1000
	s_cbranch_scc1 .Lat_y_qk
	s_mov_b32 s9, 0x10000
	v_add_u32_e32 v230, s9, v232
	v_add_u32_e32 v247, s9, v233
	v_add_u32_e32 v228, s9, v246
	v_add_u32_e32 v245, s9, v249
	ds_read_b128 v[194:197], v230
	ds_read_b128 v[198:201], v230 offset:4096
	ds_read_b128 v[202:205], v230 offset:8192
	ds_read_b128 v[206:209], v230 offset:12288
	ds_read_b128 v[210:213], v247
	ds_read_b128 v[214:217], v247 offset:4096
